# BM selected-attention fast path: scale/bias pk_fma of tile t+1 issued before the exps of tile t; hazard s_nop before the PV MFMAs dropped
# baseline (speedup 1.0000x reference)
.Lbm2_nostag:
.Lbm2_blkA:
	s_lshl_b32 s12, s15, 12
	s_add_u32 s30, s46, s12
	s_addc_u32 s31, s47, 0
	global_load_dwordx4 v[20:23], v79, s[30:31]
	global_load_dwordx4 v[24:27], v79, s[30:31] offset:1024
	global_load_dwordx4 v[28:31], v79, s[30:31] offset:2048
	global_load_dwordx4 v[32:35], v79, s[30:31] offset:3072
	s_lshl_b32 s12, s15, 12
	s_add_u32 s30, s62, s12
	s_addc_u32 s31, s63, 0
	global_load_dwordx4 v[52:55], v79, s[30:31]
	global_load_dwordx4 v[56:59], v79, s[30:31] offset:1024
	global_load_dwordx4 v[60:63], v79, s[30:31] offset:2048
	global_load_dwordx4 v[64:67], v79, s[30:31] offset:3072
	s_add_i32 s14, s35, 2
	s_add_i32 s13, s25, -1
	s_min_i32 s14, s14, s13
	s_lshl_b32 s13, s14, 2
	s_add_i32 s13, s13, s96
	v_mov_b32_e32 v76, s13
	ds_read_b32 v76, v76 offset:16384
	s_cmp_ge_i32 s54, s21
	s_cselect_b32 s14, 1, 0
	s_bfe_u32 s29, s48, 0x40000
	s_cmp_eq_u32 s29, 0
	s_cbranch_scc1 .Lbm2_Ag0_skip
	s_waitcnt vmcnt(12)
	v_mfma_f32_16x16x32_fp8_fp8 v[84:87], v[2:3], v[164:165], 0
	v_mfma_f32_16x16x32_fp8_fp8 v[88:91], v[6:7], v[164:165], 0
	v_mfma_f32_16x16x32_fp8_fp8 v[92:95], v[12:13], v[164:165], 0
	v_mfma_f32_16x16x32_fp8_fp8 v[96:99], v[16:17], v[164:165], 0
	v_mfma_f32_16x16x32_fp8_fp8 v[84:87], v[4:5], v[166:167], v[84:87]
	v_mfma_f32_16x16x32_fp8_fp8 v[88:91], v[8:9], v[166:167], v[88:91]
	v_mfma_f32_16x16x32_fp8_fp8 v[92:95], v[14:15], v[166:167], v[92:95]
	v_mfma_f32_16x16x32_fp8_fp8 v[96:99], v[18:19], v[166:167], v[96:99]
	v_and_b32_e32 v199, s29, v244
	s_cmp_eq_u32 s14, 1
	v_cmp_ne_u32_e32 vcc, 0, v199
	s_cbranch_scc1 .Lbm2_Ag0_near
	v_add_f32_e32 v200, v81, v190
	v_cndmask_b32_e32 v200, v77, v200, vcc
	s_cmp_eq_u32 s35, 0
	s_cbranch_scc1 .Lbm2_Ag0_first
	v_pk_fma_f32 v[84:85], v[84:85], s[16:17], v[200:201] op_sel_hi:[1,1,0]
	v_pk_fma_f32 v[86:87], v[86:87], s[16:17], v[200:201] op_sel_hi:[1,1,0]
	v_pk_fma_f32 v[88:89], v[88:89], s[16:17], v[200:201] op_sel_hi:[1,1,0]
	v_pk_fma_f32 v[90:91], v[90:91], s[16:17], v[200:201] op_sel_hi:[1,1,0]
	v_exp_f32_e32 v84, v84
	v_exp_f32_e32 v85, v85
	v_exp_f32_e32 v86, v86
	v_exp_f32_e32 v87, v87
	v_pk_fma_f32 v[92:93], v[92:93], s[16:17], v[200:201] op_sel_hi:[1,1,0]
	v_pk_fma_f32 v[94:95], v[94:95], s[16:17], v[200:201] op_sel_hi:[1,1,0]
	v_exp_f32_e32 v88, v88
	v_exp_f32_e32 v89, v89
	v_exp_f32_e32 v90, v90
	v_exp_f32_e32 v91, v91
	v_pk_fma_f32 v[96:97], v[96:97], s[16:17], v[200:201] op_sel_hi:[1,1,0]
	v_pk_fma_f32 v[98:99], v[98:99], s[16:17], v[200:201] op_sel_hi:[1,1,0]
	v_exp_f32_e32 v92, v92
	v_exp_f32_e32 v93, v93
	v_exp_f32_e32 v94, v94
	v_exp_f32_e32 v95, v95
	s_nop 0
	v_exp_f32_e32 v96, v96
	v_exp_f32_e32 v97, v97
	v_exp_f32_e32 v98, v98
	v_exp_f32_e32 v99, v99
	v_pk_add_f32 v[248:249], v[84:85], v[86:87]
	v_pk_add_f32 v[82:83], v[88:89], v[90:91]
	v_pk_add_f32 v[172:173], v[92:93], v[94:95]
	v_pk_add_f32 v[202:203], v[96:97], v[98:99]
	v_cvt_pk_fp8_f32 v84, v84, v85
	v_cvt_pk_fp8_f32 v85, v88, v89
	v_pk_add_f32 v[248:249], v[248:249], v[82:83]
	v_pk_add_f32 v[172:173], v[172:173], v[202:203]
	v_cvt_pk_fp8_f32 v84, v86, v87 op_sel:[0,0,1]
	v_cvt_pk_fp8_f32 v85, v90, v91 op_sel:[0,0,1]
	v_pk_add_f32 v[248:249], v[248:249], v[172:173]
	v_cvt_pk_fp8_f32 v86, v92, v93
	v_cvt_pk_fp8_f32 v87, v96, v97
	v_add_f32_e32 v248, v248, v249
	v_cvt_pk_fp8_f32 v86, v94, v95 op_sel:[0,0,1]
	v_cvt_pk_fp8_f32 v87, v98, v99 op_sel:[0,0,1]
	v_cmp_lt_f32_e32 vcc, 0x43800000, v248
	s_cbranch_vccnz .Lbm2_Ag0_redo
	v_add_f32_e32 v194, v194, v248
	s_waitcnt vmcnt(8)
	v_mfma_f32_16x16x32_fp8_fp8 v[100:103], v[36:37], v[84:85], v[100:103]
	v_mfma_f32_16x16x32_fp8_fp8 v[104:107], v[38:39], v[84:85], v[104:107]
	v_mfma_f32_16x16x32_fp8_fp8 v[108:111], v[40:41], v[84:85], v[108:111]
	v_mfma_f32_16x16x32_fp8_fp8 v[112:115], v[42:43], v[84:85], v[112:115]
	v_mfma_f32_16x16x32_fp8_fp8 v[100:103], v[44:45], v[86:87], v[100:103]
	v_mfma_f32_16x16x32_fp8_fp8 v[104:107], v[46:47], v[86:87], v[104:107]
	v_mfma_f32_16x16x32_fp8_fp8 v[108:111], v[48:49], v[86:87], v[108:111]
	v_mfma_f32_16x16x32_fp8_fp8 v[112:115], v[50:51], v[86:87], v[112:115]
	s_branch .Lbm2_Ag0_skip

.Lbm2_Ag0_first:
	v_pk_fma_f32 v[84:85], v[84:85], s[16:17], v[200:201] op_sel_hi:[1,1,0]
	v_pk_fma_f32 v[86:87], v[86:87], s[16:17], v[200:201] op_sel_hi:[1,1,0]
	v_pk_fma_f32 v[88:89], v[88:89], s[16:17], v[200:201] op_sel_hi:[1,1,0]
	v_pk_fma_f32 v[90:91], v[90:91], s[16:17], v[200:201] op_sel_hi:[1,1,0]
	v_pk_fma_f32 v[92:93], v[92:93], s[16:17], v[200:201] op_sel_hi:[1,1,0]
	v_pk_fma_f32 v[94:95], v[94:95], s[16:17], v[200:201] op_sel_hi:[1,1,0]
	v_pk_fma_f32 v[96:97], v[96:97], s[16:17], v[200:201] op_sel_hi:[1,1,0]
	v_pk_fma_f32 v[98:99], v[98:99], s[16:17], v[200:201] op_sel_hi:[1,1,0]

.Lbm2_Ag0_skip:
	s_bfe_u32 s29, s48, 0x40004
	s_cmp_eq_u32 s29, 0
	s_cbranch_scc1 .Lbm2_Ag1_skip
	s_waitcnt vmcnt(12)
	v_mfma_f32_16x16x32_fp8_fp8 v[84:87], v[2:3], v[168:169], 0
	v_mfma_f32_16x16x32_fp8_fp8 v[88:91], v[6:7], v[168:169], 0
	v_mfma_f32_16x16x32_fp8_fp8 v[92:95], v[12:13], v[168:169], 0
	v_mfma_f32_16x16x32_fp8_fp8 v[96:99], v[16:17], v[168:169], 0
	v_mfma_f32_16x16x32_fp8_fp8 v[84:87], v[4:5], v[170:171], v[84:87]
	v_mfma_f32_16x16x32_fp8_fp8 v[88:91], v[8:9], v[170:171], v[88:91]
	v_mfma_f32_16x16x32_fp8_fp8 v[92:95], v[14:15], v[170:171], v[92:95]
	v_mfma_f32_16x16x32_fp8_fp8 v[96:99], v[18:19], v[170:171], v[96:99]
	v_and_b32_e32 v199, s29, v244
	s_cmp_eq_u32 s14, 1
	v_cmp_ne_u32_e32 vcc, 0, v199
	s_cbranch_scc1 .Lbm2_Ag1_near
	v_add_f32_e32 v200, v81, v191
	v_cndmask_b32_e32 v200, v77, v200, vcc
	s_cmp_eq_u32 s35, 0
	s_cbranch_scc1 .Lbm2_Ag1_first
	v_pk_fma_f32 v[84:85], v[84:85], s[16:17], v[200:201] op_sel_hi:[1,1,0]
	v_pk_fma_f32 v[86:87], v[86:87], s[16:17], v[200:201] op_sel_hi:[1,1,0]
	v_pk_fma_f32 v[88:89], v[88:89], s[16:17], v[200:201] op_sel_hi:[1,1,0]
	v_pk_fma_f32 v[90:91], v[90:91], s[16:17], v[200:201] op_sel_hi:[1,1,0]
	v_exp_f32_e32 v84, v84
	v_exp_f32_e32 v85, v85
	v_exp_f32_e32 v86, v86
	v_exp_f32_e32 v87, v87
	v_pk_fma_f32 v[92:93], v[92:93], s[16:17], v[200:201] op_sel_hi:[1,1,0]
	v_pk_fma_f32 v[94:95], v[94:95], s[16:17], v[200:201] op_sel_hi:[1,1,0]
	v_exp_f32_e32 v88, v88
	v_exp_f32_e32 v89, v89
	v_exp_f32_e32 v90, v90
	v_exp_f32_e32 v91, v91
	v_pk_fma_f32 v[96:97], v[96:97], s[16:17], v[200:201] op_sel_hi:[1,1,0]
	v_pk_fma_f32 v[98:99], v[98:99], s[16:17], v[200:201] op_sel_hi:[1,1,0]
	v_exp_f32_e32 v92, v92
	v_exp_f32_e32 v93, v93
	v_exp_f32_e32 v94, v94
	v_exp_f32_e32 v95, v95
	s_nop 0
	v_exp_f32_e32 v96, v96
	v_exp_f32_e32 v97, v97
	v_exp_f32_e32 v98, v98
	v_exp_f32_e32 v99, v99
	v_pk_add_f32 v[248:249], v[84:85], v[86:87]
	v_pk_add_f32 v[82:83], v[88:89], v[90:91]
	v_pk_add_f32 v[172:173], v[92:93], v[94:95]
	v_pk_add_f32 v[202:203], v[96:97], v[98:99]
	v_cvt_pk_fp8_f32 v84, v84, v85
	v_cvt_pk_fp8_f32 v85, v88, v89
	v_pk_add_f32 v[248:249], v[248:249], v[82:83]
	v_pk_add_f32 v[172:173], v[172:173], v[202:203]
	v_cvt_pk_fp8_f32 v84, v86, v87 op_sel:[0,0,1]
	v_cvt_pk_fp8_f32 v85, v90, v91 op_sel:[0,0,1]
	v_pk_add_f32 v[248:249], v[248:249], v[172:173]
	v_cvt_pk_fp8_f32 v86, v92, v93
	v_cvt_pk_fp8_f32 v87, v96, v97
	v_add_f32_e32 v248, v248, v249
	v_cvt_pk_fp8_f32 v86, v94, v95 op_sel:[0,0,1]
	v_cvt_pk_fp8_f32 v87, v98, v99 op_sel:[0,0,1]
	v_cmp_lt_f32_e32 vcc, 0x43800000, v248
	s_cbranch_vccnz .Lbm2_Ag1_redo
	v_add_f32_e32 v195, v195, v248
	s_waitcnt vmcnt(8)
	v_mfma_f32_16x16x32_fp8_fp8 v[116:119], v[36:37], v[84:85], v[116:119]
	v_mfma_f32_16x16x32_fp8_fp8 v[120:123], v[38:39], v[84:85], v[120:123]
	v_mfma_f32_16x16x32_fp8_fp8 v[124:127], v[40:41], v[84:85], v[124:127]
	v_mfma_f32_16x16x32_fp8_fp8 v[128:131], v[42:43], v[84:85], v[128:131]
	v_mfma_f32_16x16x32_fp8_fp8 v[116:119], v[44:45], v[86:87], v[116:119]
	v_mfma_f32_16x16x32_fp8_fp8 v[120:123], v[46:47], v[86:87], v[120:123]
	v_mfma_f32_16x16x32_fp8_fp8 v[124:127], v[48:49], v[86:87], v[124:127]
	v_mfma_f32_16x16x32_fp8_fp8 v[128:131], v[50:51], v[86:87], v[128:131]
	s_branch .Lbm2_Ag1_skip

.Lbm2_Ag1_skip:
	s_bfe_u32 s29, s48, 0x40008
	s_cmp_eq_u32 s29, 0
	s_cbranch_scc1 .Lbm2_Ag2_skip
	s_waitcnt vmcnt(12)
	v_mfma_f32_16x16x32_fp8_fp8 v[84:87], v[2:3], v[182:183], 0
	v_mfma_f32_16x16x32_fp8_fp8 v[88:91], v[6:7], v[182:183], 0
	v_mfma_f32_16x16x32_fp8_fp8 v[92:95], v[12:13], v[182:183], 0
	v_mfma_f32_16x16x32_fp8_fp8 v[96:99], v[16:17], v[182:183], 0
	v_mfma_f32_16x16x32_fp8_fp8 v[84:87], v[4:5], v[184:185], v[84:87]
	v_mfma_f32_16x16x32_fp8_fp8 v[88:91], v[8:9], v[184:185], v[88:91]
	v_mfma_f32_16x16x32_fp8_fp8 v[92:95], v[14:15], v[184:185], v[92:95]
	v_mfma_f32_16x16x32_fp8_fp8 v[96:99], v[18:19], v[184:185], v[96:99]
	v_and_b32_e32 v199, s29, v244
	s_cmp_eq_u32 s14, 1
	v_cmp_ne_u32_e32 vcc, 0, v199
	s_cbranch_scc1 .Lbm2_Ag2_near
	v_add_f32_e32 v200, v81, v192
	v_cndmask_b32_e32 v200, v77, v200, vcc
	s_cmp_eq_u32 s35, 0
	s_cbranch_scc1 .Lbm2_Ag2_first
	v_pk_fma_f32 v[84:85], v[84:85], s[16:17], v[200:201] op_sel_hi:[1,1,0]
	v_pk_fma_f32 v[86:87], v[86:87], s[16:17], v[200:201] op_sel_hi:[1,1,0]
	v_pk_fma_f32 v[88:89], v[88:89], s[16:17], v[200:201] op_sel_hi:[1,1,0]
	v_pk_fma_f32 v[90:91], v[90:91], s[16:17], v[200:201] op_sel_hi:[1,1,0]
	v_exp_f32_e32 v84, v84
	v_exp_f32_e32 v85, v85
	v_exp_f32_e32 v86, v86
	v_exp_f32_e32 v87, v87
	v_pk_fma_f32 v[92:93], v[92:93], s[16:17], v[200:201] op_sel_hi:[1,1,0]
	v_pk_fma_f32 v[94:95], v[94:95], s[16:17], v[200:201] op_sel_hi:[1,1,0]
	v_exp_f32_e32 v88, v88
	v_exp_f32_e32 v89, v89
	v_exp_f32_e32 v90, v90
	v_exp_f32_e32 v91, v91
	v_pk_fma_f32 v[96:97], v[96:97], s[16:17], v[200:201] op_sel_hi:[1,1,0]
	v_pk_fma_f32 v[98:99], v[98:99], s[16:17], v[200:201] op_sel_hi:[1,1,0]
	v_exp_f32_e32 v92, v92
	v_exp_f32_e32 v93, v93
	v_exp_f32_e32 v94, v94
	v_exp_f32_e32 v95, v95
	s_nop 0
	v_exp_f32_e32 v96, v96
	v_exp_f32_e32 v97, v97
	v_exp_f32_e32 v98, v98
	v_exp_f32_e32 v99, v99
	v_pk_add_f32 v[248:249], v[84:85], v[86:87]
	v_pk_add_f32 v[82:83], v[88:89], v[90:91]
	v_pk_add_f32 v[172:173], v[92:93], v[94:95]
	v_pk_add_f32 v[202:203], v[96:97], v[98:99]
	v_cvt_pk_fp8_f32 v84, v84, v85
	v_cvt_pk_fp8_f32 v85, v88, v89
	v_pk_add_f32 v[248:249], v[248:249], v[82:83]
	v_pk_add_f32 v[172:173], v[172:173], v[202:203]
	v_cvt_pk_fp8_f32 v84, v86, v87 op_sel:[0,0,1]
	v_cvt_pk_fp8_f32 v85, v90, v91 op_sel:[0,0,1]
	v_pk_add_f32 v[248:249], v[248:249], v[172:173]
	v_cvt_pk_fp8_f32 v86, v92, v93
	v_cvt_pk_fp8_f32 v87, v96, v97
	v_add_f32_e32 v248, v248, v249
	v_cvt_pk_fp8_f32 v86, v94, v95 op_sel:[0,0,1]
	v_cvt_pk_fp8_f32 v87, v98, v99 op_sel:[0,0,1]
	v_cmp_lt_f32_e32 vcc, 0x43800000, v248
	s_cbranch_vccnz .Lbm2_Ag2_redo
	v_add_f32_e32 v196, v196, v248
	s_waitcnt vmcnt(8)
	v_mfma_f32_16x16x32_fp8_fp8 v[132:135], v[36:37], v[84:85], v[132:135]
	v_mfma_f32_16x16x32_fp8_fp8 v[136:139], v[38:39], v[84:85], v[136:139]
	v_mfma_f32_16x16x32_fp8_fp8 v[140:143], v[40:41], v[84:85], v[140:143]
	v_mfma_f32_16x16x32_fp8_fp8 v[144:147], v[42:43], v[84:85], v[144:147]
	v_mfma_f32_16x16x32_fp8_fp8 v[132:135], v[44:45], v[86:87], v[132:135]
	v_mfma_f32_16x16x32_fp8_fp8 v[136:139], v[46:47], v[86:87], v[136:139]
	v_mfma_f32_16x16x32_fp8_fp8 v[140:143], v[48:49], v[86:87], v[140:143]
	v_mfma_f32_16x16x32_fp8_fp8 v[144:147], v[50:51], v[86:87], v[144:147]
	s_branch .Lbm2_Ag2_skip

.Lbm2_Ag2_skip:
	s_bfe_u32 s29, s48, 0x4000c
	s_cmp_eq_u32 s29, 0
	s_cbranch_scc1 .Lbm2_Ag3_skip
	s_waitcnt vmcnt(12)
	v_mfma_f32_16x16x32_fp8_fp8 v[84:87], v[2:3], v[186:187], 0
	v_mfma_f32_16x16x32_fp8_fp8 v[88:91], v[6:7], v[186:187], 0
	v_mfma_f32_16x16x32_fp8_fp8 v[92:95], v[12:13], v[186:187], 0
	v_mfma_f32_16x16x32_fp8_fp8 v[96:99], v[16:17], v[186:187], 0
	v_mfma_f32_16x16x32_fp8_fp8 v[84:87], v[4:5], v[188:189], v[84:87]
	v_mfma_f32_16x16x32_fp8_fp8 v[88:91], v[8:9], v[188:189], v[88:91]
	v_mfma_f32_16x16x32_fp8_fp8 v[92:95], v[14:15], v[188:189], v[92:95]
	v_mfma_f32_16x16x32_fp8_fp8 v[96:99], v[18:19], v[188:189], v[96:99]
	v_and_b32_e32 v199, s29, v244
	s_cmp_eq_u32 s14, 1
	v_cmp_ne_u32_e32 vcc, 0, v199
	s_cbranch_scc1 .Lbm2_Ag3_near
	v_add_f32_e32 v200, v81, v193
	v_cndmask_b32_e32 v200, v77, v200, vcc
	s_cmp_eq_u32 s35, 0
	s_cbranch_scc1 .Lbm2_Ag3_first
	v_pk_fma_f32 v[84:85], v[84:85], s[16:17], v[200:201] op_sel_hi:[1,1,0]
	v_pk_fma_f32 v[86:87], v[86:87], s[16:17], v[200:201] op_sel_hi:[1,1,0]
	v_pk_fma_f32 v[88:89], v[88:89], s[16:17], v[200:201] op_sel_hi:[1,1,0]
	v_pk_fma_f32 v[90:91], v[90:91], s[16:17], v[200:201] op_sel_hi:[1,1,0]
	v_exp_f32_e32 v84, v84
	v_exp_f32_e32 v85, v85
	v_exp_f32_e32 v86, v86
	v_exp_f32_e32 v87, v87
	v_pk_fma_f32 v[92:93], v[92:93], s[16:17], v[200:201] op_sel_hi:[1,1,0]
	v_pk_fma_f32 v[94:95], v[94:95], s[16:17], v[200:201] op_sel_hi:[1,1,0]
	v_exp_f32_e32 v88, v88
	v_exp_f32_e32 v89, v89
	v_exp_f32_e32 v90, v90
	v_exp_f32_e32 v91, v91
	v_pk_fma_f32 v[96:97], v[96:97], s[16:17], v[200:201] op_sel_hi:[1,1,0]
	v_pk_fma_f32 v[98:99], v[98:99], s[16:17], v[200:201] op_sel_hi:[1,1,0]
	v_exp_f32_e32 v92, v92
	v_exp_f32_e32 v93, v93
	v_exp_f32_e32 v94, v94
	v_exp_f32_e32 v95, v95
	s_nop 0
	v_exp_f32_e32 v96, v96
	v_exp_f32_e32 v97, v97
	v_exp_f32_e32 v98, v98
	v_exp_f32_e32 v99, v99
	v_pk_add_f32 v[248:249], v[84:85], v[86:87]
	v_pk_add_f32 v[82:83], v[88:89], v[90:91]
	v_pk_add_f32 v[172:173], v[92:93], v[94:95]
	v_pk_add_f32 v[202:203], v[96:97], v[98:99]
	v_cvt_pk_fp8_f32 v84, v84, v85
	v_cvt_pk_fp8_f32 v85, v88, v89
	v_pk_add_f32 v[248:249], v[248:249], v[82:83]
	v_pk_add_f32 v[172:173], v[172:173], v[202:203]
	v_cvt_pk_fp8_f32 v84, v86, v87 op_sel:[0,0,1]
	v_cvt_pk_fp8_f32 v85, v90, v91 op_sel:[0,0,1]
	v_pk_add_f32 v[248:249], v[248:249], v[172:173]
	v_cvt_pk_fp8_f32 v86, v92, v93
	v_cvt_pk_fp8_f32 v87, v96, v97
	v_add_f32_e32 v248, v248, v249
	v_cvt_pk_fp8_f32 v86, v94, v95 op_sel:[0,0,1]
	v_cvt_pk_fp8_f32 v87, v98, v99 op_sel:[0,0,1]
	v_cmp_lt_f32_e32 vcc, 0x43800000, v248
	s_cbranch_vccnz .Lbm2_Ag3_redo
	v_add_f32_e32 v197, v197, v248
	s_waitcnt vmcnt(8)
	v_mfma_f32_16x16x32_fp8_fp8 v[148:151], v[36:37], v[84:85], v[148:151]
	v_mfma_f32_16x16x32_fp8_fp8 v[152:155], v[38:39], v[84:85], v[152:155]
	v_mfma_f32_16x16x32_fp8_fp8 v[156:159], v[40:41], v[84:85], v[156:159]
	v_mfma_f32_16x16x32_fp8_fp8 v[160:163], v[42:43], v[84:85], v[160:163]
	v_mfma_f32_16x16x32_fp8_fp8 v[148:151], v[44:45], v[86:87], v[148:151]
	v_mfma_f32_16x16x32_fp8_fp8 v[152:155], v[46:47], v[86:87], v[152:155]
	v_mfma_f32_16x16x32_fp8_fp8 v[156:159], v[48:49], v[86:87], v[156:159]
	v_mfma_f32_16x16x32_fp8_fp8 v[160:163], v[50:51], v[86:87], v[160:163]
	s_branch .Lbm2_Ag3_skip

.Lbm2_blkB:
	s_lshl_b32 s12, s15, 12
	s_add_u32 s30, s46, s12
	s_addc_u32 s31, s47, 0
	global_load_dwordx4 v[2:5], v79, s[30:31]
	global_load_dwordx4 v[6:9], v79, s[30:31] offset:1024
	global_load_dwordx4 v[12:15], v79, s[30:31] offset:2048
	global_load_dwordx4 v[16:19], v79, s[30:31] offset:3072
	s_lshl_b32 s12, s15, 12
	s_add_u32 s30, s62, s12
	s_addc_u32 s31, s63, 0
	global_load_dwordx4 v[36:39], v79, s[30:31]
	global_load_dwordx4 v[40:43], v79, s[30:31] offset:1024
	global_load_dwordx4 v[44:47], v79, s[30:31] offset:2048
	global_load_dwordx4 v[48:51], v79, s[30:31] offset:3072
	s_add_i32 s14, s35, 2
	s_add_i32 s13, s25, -1
	s_min_i32 s14, s14, s13
	s_lshl_b32 s13, s14, 2
	s_add_i32 s13, s13, s96
	v_mov_b32_e32 v76, s13
	ds_read_b32 v76, v76 offset:16384
	s_cmp_ge_i32 s54, s21
	s_cselect_b32 s14, 1, 0
	s_bfe_u32 s29, s48, 0x40000
	s_cmp_eq_u32 s29, 0
	s_cbranch_scc1 .Lbm2_Bg0_skip
	s_waitcnt vmcnt(12)
	v_mfma_f32_16x16x32_fp8_fp8 v[84:87], v[20:21], v[164:165], 0
	v_mfma_f32_16x16x32_fp8_fp8 v[88:91], v[24:25], v[164:165], 0
	v_mfma_f32_16x16x32_fp8_fp8 v[92:95], v[28:29], v[164:165], 0
	v_mfma_f32_16x16x32_fp8_fp8 v[96:99], v[32:33], v[164:165], 0
	v_mfma_f32_16x16x32_fp8_fp8 v[84:87], v[22:23], v[166:167], v[84:87]
	v_mfma_f32_16x16x32_fp8_fp8 v[88:91], v[26:27], v[166:167], v[88:91]
	v_mfma_f32_16x16x32_fp8_fp8 v[92:95], v[30:31], v[166:167], v[92:95]
	v_mfma_f32_16x16x32_fp8_fp8 v[96:99], v[34:35], v[166:167], v[96:99]
	v_and_b32_e32 v199, s29, v244
	s_cmp_eq_u32 s14, 1
	v_cmp_ne_u32_e32 vcc, 0, v199
	s_cbranch_scc1 .Lbm2_Bg0_near
	v_add_f32_e32 v200, v81, v190
	v_cndmask_b32_e32 v200, v77, v200, vcc
	s_cmp_eq_u32 s35, 0
	s_cbranch_scc1 .Lbm2_Bg0_first
	v_pk_fma_f32 v[84:85], v[84:85], s[16:17], v[200:201] op_sel_hi:[1,1,0]
	v_pk_fma_f32 v[86:87], v[86:87], s[16:17], v[200:201] op_sel_hi:[1,1,0]
	v_pk_fma_f32 v[88:89], v[88:89], s[16:17], v[200:201] op_sel_hi:[1,1,0]
	v_pk_fma_f32 v[90:91], v[90:91], s[16:17], v[200:201] op_sel_hi:[1,1,0]
	v_exp_f32_e32 v84, v84
	v_exp_f32_e32 v85, v85
	v_exp_f32_e32 v86, v86
	v_exp_f32_e32 v87, v87
	v_pk_fma_f32 v[92:93], v[92:93], s[16:17], v[200:201] op_sel_hi:[1,1,0]
	v_pk_fma_f32 v[94:95], v[94:95], s[16:17], v[200:201] op_sel_hi:[1,1,0]
	v_exp_f32_e32 v88, v88
	v_exp_f32_e32 v89, v89
	v_exp_f32_e32 v90, v90
	v_exp_f32_e32 v91, v91
	v_pk_fma_f32 v[96:97], v[96:97], s[16:17], v[200:201] op_sel_hi:[1,1,0]
	v_pk_fma_f32 v[98:99], v[98:99], s[16:17], v[200:201] op_sel_hi:[1,1,0]
	v_exp_f32_e32 v92, v92
	v_exp_f32_e32 v93, v93
	v_exp_f32_e32 v94, v94
	v_exp_f32_e32 v95, v95
	s_nop 0
	v_exp_f32_e32 v96, v96
	v_exp_f32_e32 v97, v97
	v_exp_f32_e32 v98, v98
	v_exp_f32_e32 v99, v99
	v_pk_add_f32 v[248:249], v[84:85], v[86:87]
	v_pk_add_f32 v[82:83], v[88:89], v[90:91]
	v_pk_add_f32 v[172:173], v[92:93], v[94:95]
	v_pk_add_f32 v[202:203], v[96:97], v[98:99]
	v_cvt_pk_fp8_f32 v84, v84, v85
	v_cvt_pk_fp8_f32 v85, v88, v89
	v_pk_add_f32 v[248:249], v[248:249], v[82:83]
	v_pk_add_f32 v[172:173], v[172:173], v[202:203]
	v_cvt_pk_fp8_f32 v84, v86, v87 op_sel:[0,0,1]
	v_cvt_pk_fp8_f32 v85, v90, v91 op_sel:[0,0,1]
	v_pk_add_f32 v[248:249], v[248:249], v[172:173]
	v_cvt_pk_fp8_f32 v86, v92, v93
	v_cvt_pk_fp8_f32 v87, v96, v97
	v_add_f32_e32 v248, v248, v249
	v_cvt_pk_fp8_f32 v86, v94, v95 op_sel:[0,0,1]
	v_cvt_pk_fp8_f32 v87, v98, v99 op_sel:[0,0,1]
	v_cmp_lt_f32_e32 vcc, 0x43800000, v248
	s_cbranch_vccnz .Lbm2_Bg0_redo
	v_add_f32_e32 v194, v194, v248
	s_waitcnt vmcnt(8)
	v_mfma_f32_16x16x32_fp8_fp8 v[100:103], v[52:53], v[84:85], v[100:103]
	v_mfma_f32_16x16x32_fp8_fp8 v[104:107], v[54:55], v[84:85], v[104:107]
	v_mfma_f32_16x16x32_fp8_fp8 v[108:111], v[56:57], v[84:85], v[108:111]
	v_mfma_f32_16x16x32_fp8_fp8 v[112:115], v[58:59], v[84:85], v[112:115]
	v_mfma_f32_16x16x32_fp8_fp8 v[100:103], v[60:61], v[86:87], v[100:103]
	v_mfma_f32_16x16x32_fp8_fp8 v[104:107], v[62:63], v[86:87], v[104:107]
	v_mfma_f32_16x16x32_fp8_fp8 v[108:111], v[64:65], v[86:87], v[108:111]
	v_mfma_f32_16x16x32_fp8_fp8 v[112:115], v[66:67], v[86:87], v[112:115]
	s_branch .Lbm2_Bg0_skip

.Lbm2_Bg0_skip:
	s_bfe_u32 s29, s48, 0x40004
	s_cmp_eq_u32 s29, 0
	s_cbranch_scc1 .Lbm2_Bg1_skip
	s_waitcnt vmcnt(12)
	v_mfma_f32_16x16x32_fp8_fp8 v[84:87], v[20:21], v[168:169], 0
	v_mfma_f32_16x16x32_fp8_fp8 v[88:91], v[24:25], v[168:169], 0
	v_mfma_f32_16x16x32_fp8_fp8 v[92:95], v[28:29], v[168:169], 0
	v_mfma_f32_16x16x32_fp8_fp8 v[96:99], v[32:33], v[168:169], 0
	v_mfma_f32_16x16x32_fp8_fp8 v[84:87], v[22:23], v[170:171], v[84:87]
	v_mfma_f32_16x16x32_fp8_fp8 v[88:91], v[26:27], v[170:171], v[88:91]
	v_mfma_f32_16x16x32_fp8_fp8 v[92:95], v[30:31], v[170:171], v[92:95]
	v_mfma_f32_16x16x32_fp8_fp8 v[96:99], v[34:35], v[170:171], v[96:99]
	v_and_b32_e32 v199, s29, v244
	s_cmp_eq_u32 s14, 1
	v_cmp_ne_u32_e32 vcc, 0, v199
	s_cbranch_scc1 .Lbm2_Bg1_near
	v_add_f32_e32 v200, v81, v191
	v_cndmask_b32_e32 v200, v77, v200, vcc
	s_cmp_eq_u32 s35, 0
	s_cbranch_scc1 .Lbm2_Bg1_first
	v_pk_fma_f32 v[84:85], v[84:85], s[16:17], v[200:201] op_sel_hi:[1,1,0]
	v_pk_fma_f32 v[86:87], v[86:87], s[16:17], v[200:201] op_sel_hi:[1,1,0]
	v_pk_fma_f32 v[88:89], v[88:89], s[16:17], v[200:201] op_sel_hi:[1,1,0]
	v_pk_fma_f32 v[90:91], v[90:91], s[16:17], v[200:201] op_sel_hi:[1,1,0]
	v_exp_f32_e32 v84, v84
	v_exp_f32_e32 v85, v85
	v_exp_f32_e32 v86, v86
	v_exp_f32_e32 v87, v87
	v_pk_fma_f32 v[92:93], v[92:93], s[16:17], v[200:201] op_sel_hi:[1,1,0]
	v_pk_fma_f32 v[94:95], v[94:95], s[16:17], v[200:201] op_sel_hi:[1,1,0]
	v_exp_f32_e32 v88, v88
	v_exp_f32_e32 v89, v89
	v_exp_f32_e32 v90, v90
	v_exp_f32_e32 v91, v91
	v_pk_fma_f32 v[96:97], v[96:97], s[16:17], v[200:201] op_sel_hi:[1,1,0]
	v_pk_fma_f32 v[98:99], v[98:99], s[16:17], v[200:201] op_sel_hi:[1,1,0]
	v_exp_f32_e32 v92, v92
	v_exp_f32_e32 v93, v93
	v_exp_f32_e32 v94, v94
	v_exp_f32_e32 v95, v95
	s_nop 0
	v_exp_f32_e32 v96, v96
	v_exp_f32_e32 v97, v97
	v_exp_f32_e32 v98, v98
	v_exp_f32_e32 v99, v99
	v_pk_add_f32 v[248:249], v[84:85], v[86:87]
	v_pk_add_f32 v[82:83], v[88:89], v[90:91]
	v_pk_add_f32 v[172:173], v[92:93], v[94:95]
	v_pk_add_f32 v[202:203], v[96:97], v[98:99]
	v_cvt_pk_fp8_f32 v84, v84, v85
	v_cvt_pk_fp8_f32 v85, v88, v89
	v_pk_add_f32 v[248:249], v[248:249], v[82:83]
	v_pk_add_f32 v[172:173], v[172:173], v[202:203]
	v_cvt_pk_fp8_f32 v84, v86, v87 op_sel:[0,0,1]
	v_cvt_pk_fp8_f32 v85, v90, v91 op_sel:[0,0,1]
	v_pk_add_f32 v[248:249], v[248:249], v[172:173]
	v_cvt_pk_fp8_f32 v86, v92, v93
	v_cvt_pk_fp8_f32 v87, v96, v97
	v_add_f32_e32 v248, v248, v249
	v_cvt_pk_fp8_f32 v86, v94, v95 op_sel:[0,0,1]
	v_cvt_pk_fp8_f32 v87, v98, v99 op_sel:[0,0,1]
	v_cmp_lt_f32_e32 vcc, 0x43800000, v248
	s_cbranch_vccnz .Lbm2_Bg1_redo
	v_add_f32_e32 v195, v195, v248
	s_waitcnt vmcnt(8)
	v_mfma_f32_16x16x32_fp8_fp8 v[116:119], v[52:53], v[84:85], v[116:119]
	v_mfma_f32_16x16x32_fp8_fp8 v[120:123], v[54:55], v[84:85], v[120:123]
	v_mfma_f32_16x16x32_fp8_fp8 v[124:127], v[56:57], v[84:85], v[124:127]
	v_mfma_f32_16x16x32_fp8_fp8 v[128:131], v[58:59], v[84:85], v[128:131]
	v_mfma_f32_16x16x32_fp8_fp8 v[116:119], v[60:61], v[86:87], v[116:119]
	v_mfma_f32_16x16x32_fp8_fp8 v[120:123], v[62:63], v[86:87], v[120:123]
	v_mfma_f32_16x16x32_fp8_fp8 v[124:127], v[64:65], v[86:87], v[124:127]
	v_mfma_f32_16x16x32_fp8_fp8 v[128:131], v[66:67], v[86:87], v[128:131]
	s_branch .Lbm2_Bg1_skip

.Lbm2_Bg1_skip:
	s_bfe_u32 s29, s48, 0x40008
	s_cmp_eq_u32 s29, 0
	s_cbranch_scc1 .Lbm2_Bg2_skip
	s_waitcnt vmcnt(12)
	v_mfma_f32_16x16x32_fp8_fp8 v[84:87], v[20:21], v[182:183], 0
	v_mfma_f32_16x16x32_fp8_fp8 v[88:91], v[24:25], v[182:183], 0
	v_mfma_f32_16x16x32_fp8_fp8 v[92:95], v[28:29], v[182:183], 0
	v_mfma_f32_16x16x32_fp8_fp8 v[96:99], v[32:33], v[182:183], 0
	v_mfma_f32_16x16x32_fp8_fp8 v[84:87], v[22:23], v[184:185], v[84:87]
	v_mfma_f32_16x16x32_fp8_fp8 v[88:91], v[26:27], v[184:185], v[88:91]
	v_mfma_f32_16x16x32_fp8_fp8 v[92:95], v[30:31], v[184:185], v[92:95]
	v_mfma_f32_16x16x32_fp8_fp8 v[96:99], v[34:35], v[184:185], v[96:99]
	v_and_b32_e32 v199, s29, v244
	s_cmp_eq_u32 s14, 1
	v_cmp_ne_u32_e32 vcc, 0, v199
	s_cbranch_scc1 .Lbm2_Bg2_near
	v_add_f32_e32 v200, v81, v192
	v_cndmask_b32_e32 v200, v77, v200, vcc
	s_cmp_eq_u32 s35, 0
	s_cbranch_scc1 .Lbm2_Bg2_first
	v_pk_fma_f32 v[84:85], v[84:85], s[16:17], v[200:201] op_sel_hi:[1,1,0]
	v_pk_fma_f32 v[86:87], v[86:87], s[16:17], v[200:201] op_sel_hi:[1,1,0]
	v_pk_fma_f32 v[88:89], v[88:89], s[16:17], v[200:201] op_sel_hi:[1,1,0]
	v_pk_fma_f32 v[90:91], v[90:91], s[16:17], v[200:201] op_sel_hi:[1,1,0]
	v_exp_f32_e32 v84, v84
	v_exp_f32_e32 v85, v85
	v_exp_f32_e32 v86, v86
	v_exp_f32_e32 v87, v87
	v_pk_fma_f32 v[92:93], v[92:93], s[16:17], v[200:201] op_sel_hi:[1,1,0]
	v_pk_fma_f32 v[94:95], v[94:95], s[16:17], v[200:201] op_sel_hi:[1,1,0]
	v_exp_f32_e32 v88, v88
	v_exp_f32_e32 v89, v89
	v_exp_f32_e32 v90, v90
	v_exp_f32_e32 v91, v91
	v_pk_fma_f32 v[96:97], v[96:97], s[16:17], v[200:201] op_sel_hi:[1,1,0]
	v_pk_fma_f32 v[98:99], v[98:99], s[16:17], v[200:201] op_sel_hi:[1,1,0]
	v_exp_f32_e32 v92, v92
	v_exp_f32_e32 v93, v93
	v_exp_f32_e32 v94, v94
	v_exp_f32_e32 v95, v95
	s_nop 0
	v_exp_f32_e32 v96, v96
	v_exp_f32_e32 v97, v97
	v_exp_f32_e32 v98, v98
	v_exp_f32_e32 v99, v99
	v_pk_add_f32 v[248:249], v[84:85], v[86:87]
	v_pk_add_f32 v[82:83], v[88:89], v[90:91]
	v_pk_add_f32 v[172:173], v[92:93], v[94:95]
	v_pk_add_f32 v[202:203], v[96:97], v[98:99]
	v_cvt_pk_fp8_f32 v84, v84, v85
	v_cvt_pk_fp8_f32 v85, v88, v89
	v_pk_add_f32 v[248:249], v[248:249], v[82:83]
	v_pk_add_f32 v[172:173], v[172:173], v[202:203]
	v_cvt_pk_fp8_f32 v84, v86, v87 op_sel:[0,0,1]
	v_cvt_pk_fp8_f32 v85, v90, v91 op_sel:[0,0,1]
	v_pk_add_f32 v[248:249], v[248:249], v[172:173]
	v_cvt_pk_fp8_f32 v86, v92, v93
	v_cvt_pk_fp8_f32 v87, v96, v97
	v_add_f32_e32 v248, v248, v249
	v_cvt_pk_fp8_f32 v86, v94, v95 op_sel:[0,0,1]
	v_cvt_pk_fp8_f32 v87, v98, v99 op_sel:[0,0,1]
	v_cmp_lt_f32_e32 vcc, 0x43800000, v248
	s_cbranch_vccnz .Lbm2_Bg2_redo
	v_add_f32_e32 v196, v196, v248
	s_waitcnt vmcnt(8)
	v_mfma_f32_16x16x32_fp8_fp8 v[132:135], v[52:53], v[84:85], v[132:135]
	v_mfma_f32_16x16x32_fp8_fp8 v[136:139], v[54:55], v[84:85], v[136:139]
	v_mfma_f32_16x16x32_fp8_fp8 v[140:143], v[56:57], v[84:85], v[140:143]
	v_mfma_f32_16x16x32_fp8_fp8 v[144:147], v[58:59], v[84:85], v[144:147]
	v_mfma_f32_16x16x32_fp8_fp8 v[132:135], v[60:61], v[86:87], v[132:135]
	v_mfma_f32_16x16x32_fp8_fp8 v[136:139], v[62:63], v[86:87], v[136:139]
	v_mfma_f32_16x16x32_fp8_fp8 v[140:143], v[64:65], v[86:87], v[140:143]
	v_mfma_f32_16x16x32_fp8_fp8 v[144:147], v[66:67], v[86:87], v[144:147]
	s_branch .Lbm2_Bg2_skip

.Lbm2_Bg2_skip:
	s_bfe_u32 s29, s48, 0x4000c
	s_cmp_eq_u32 s29, 0
	s_cbranch_scc1 .Lbm2_Bg3_skip
	s_waitcnt vmcnt(12)
	v_mfma_f32_16x16x32_fp8_fp8 v[84:87], v[20:21], v[186:187], 0
	v_mfma_f32_16x16x32_fp8_fp8 v[88:91], v[24:25], v[186:187], 0
	v_mfma_f32_16x16x32_fp8_fp8 v[92:95], v[28:29], v[186:187], 0
	v_mfma_f32_16x16x32_fp8_fp8 v[96:99], v[32:33], v[186:187], 0
	v_mfma_f32_16x16x32_fp8_fp8 v[84:87], v[22:23], v[188:189], v[84:87]
	v_mfma_f32_16x16x32_fp8_fp8 v[88:91], v[26:27], v[188:189], v[88:91]
	v_mfma_f32_16x16x32_fp8_fp8 v[92:95], v[30:31], v[188:189], v[92:95]
	v_mfma_f32_16x16x32_fp8_fp8 v[96:99], v[34:35], v[188:189], v[96:99]
	v_and_b32_e32 v199, s29, v244
	s_cmp_eq_u32 s14, 1
	v_cmp_ne_u32_e32 vcc, 0, v199
	s_cbranch_scc1 .Lbm2_Bg3_near
	v_add_f32_e32 v200, v81, v193
	v_cndmask_b32_e32 v200, v77, v200, vcc
	s_cmp_eq_u32 s35, 0
	s_cbranch_scc1 .Lbm2_Bg3_first
	v_pk_fma_f32 v[84:85], v[84:85], s[16:17], v[200:201] op_sel_hi:[1,1,0]
	v_pk_fma_f32 v[86:87], v[86:87], s[16:17], v[200:201] op_sel_hi:[1,1,0]
	v_pk_fma_f32 v[88:89], v[88:89], s[16:17], v[200:201] op_sel_hi:[1,1,0]
	v_pk_fma_f32 v[90:91], v[90:91], s[16:17], v[200:201] op_sel_hi:[1,1,0]
	v_exp_f32_e32 v84, v84
	v_exp_f32_e32 v85, v85
	v_exp_f32_e32 v86, v86
	v_exp_f32_e32 v87, v87
	v_pk_fma_f32 v[92:93], v[92:93], s[16:17], v[200:201] op_sel_hi:[1,1,0]
	v_pk_fma_f32 v[94:95], v[94:95], s[16:17], v[200:201] op_sel_hi:[1,1,0]
	v_exp_f32_e32 v88, v88
	v_exp_f32_e32 v89, v89
	v_exp_f32_e32 v90, v90
	v_exp_f32_e32 v91, v91
	v_pk_fma_f32 v[96:97], v[96:97], s[16:17], v[200:201] op_sel_hi:[1,1,0]
	v_pk_fma_f32 v[98:99], v[98:99], s[16:17], v[200:201] op_sel_hi:[1,1,0]
	v_exp_f32_e32 v92, v92
	v_exp_f32_e32 v93, v93
	v_exp_f32_e32 v94, v94
	v_exp_f32_e32 v95, v95
	s_nop 0
	v_exp_f32_e32 v96, v96
	v_exp_f32_e32 v97, v97
	v_exp_f32_e32 v98, v98
	v_exp_f32_e32 v99, v99
	v_pk_add_f32 v[248:249], v[84:85], v[86:87]
	v_pk_add_f32 v[82:83], v[88:89], v[90:91]
	v_pk_add_f32 v[172:173], v[92:93], v[94:95]
	v_pk_add_f32 v[202:203], v[96:97], v[98:99]
	v_cvt_pk_fp8_f32 v84, v84, v85
	v_cvt_pk_fp8_f32 v85, v88, v89
	v_pk_add_f32 v[248:249], v[248:249], v[82:83]
	v_pk_add_f32 v[172:173], v[172:173], v[202:203]
	v_cvt_pk_fp8_f32 v84, v86, v87 op_sel:[0,0,1]
	v_cvt_pk_fp8_f32 v85, v90, v91 op_sel:[0,0,1]
	v_pk_add_f32 v[248:249], v[248:249], v[172:173]
	v_cvt_pk_fp8_f32 v86, v92, v93
	v_cvt_pk_fp8_f32 v87, v96, v97
	v_add_f32_e32 v248, v248, v249
	v_cvt_pk_fp8_f32 v86, v94, v95 op_sel:[0,0,1]
	v_cvt_pk_fp8_f32 v87, v98, v99 op_sel:[0,0,1]
	v_cmp_lt_f32_e32 vcc, 0x43800000, v248
	s_cbranch_vccnz .Lbm2_Bg3_redo
	v_add_f32_e32 v197, v197, v248
	s_waitcnt vmcnt(8)
	v_mfma_f32_16x16x32_fp8_fp8 v[148:151], v[52:53], v[84:85], v[148:151]
	v_mfma_f32_16x16x32_fp8_fp8 v[152:155], v[54:55], v[84:85], v[152:155]
	v_mfma_f32_16x16x32_fp8_fp8 v[156:159], v[56:57], v[84:85], v[156:159]
	v_mfma_f32_16x16x32_fp8_fp8 v[160:163], v[58:59], v[84:85], v[160:163]
	v_mfma_f32_16x16x32_fp8_fp8 v[148:151], v[60:61], v[86:87], v[148:151]
	v_mfma_f32_16x16x32_fp8_fp8 v[152:155], v[62:63], v[86:87], v[152:155]
	v_mfma_f32_16x16x32_fp8_fp8 v[156:159], v[64:65], v[86:87], v[156:159]
	v_mfma_f32_16x16x32_fp8_fp8 v[160:163], v[66:67], v[86:87], v[160:163]
	s_branch .Lbm2_Bg3_skip

.Lbm3_nostag:
.Lbm3_blkA:
	s_lshl_b32 s29, s27, 12
	s_add_u32 s30, s40, s29
	s_addc_u32 s31, s41, 0
	global_load_dwordx4 v[20:23], v79, s[30:31]
	global_load_dwordx4 v[24:27], v79, s[30:31] offset:1024
	global_load_dwordx4 v[28:31], v79, s[30:31] offset:2048
	global_load_dwordx4 v[32:35], v79, s[30:31] offset:3072
	s_lshl_b32 s29, s27, 12
	s_add_u32 s30, s62, s29
	s_addc_u32 s31, s63, 0
	global_load_dwordx4 v[52:55], v79, s[30:31]
	global_load_dwordx4 v[56:59], v79, s[30:31] offset:1024
	global_load_dwordx4 v[60:63], v79, s[30:31] offset:2048
	global_load_dwordx4 v[64:67], v79, s[30:31] offset:3072
	s_add_i32 s50, s35, 2
	s_add_i32 s9, s25, -1
	s_min_i32 s50, s50, s9
	s_lshl_b32 s9, s50, 2
	s_add_i32 s9, s9, s46
	v_mov_b32_e32 v76, s9
	ds_read_b32 v76, v76 offset:16384
	s_cmp_ge_i32 s38, s21
	s_cselect_b32 s50, 1, 0
	s_bfe_u32 s29, s48, 0x40000
	s_cmp_eq_u32 s29, 0
	s_cbranch_scc1 .Lbm3_Ag0_skip
	s_waitcnt vmcnt(12)
	v_mfma_f32_16x16x32_fp8_fp8 v[84:87], v[2:3], v[164:165], 0
	v_mfma_f32_16x16x32_fp8_fp8 v[88:91], v[6:7], v[164:165], 0
	v_mfma_f32_16x16x32_fp8_fp8 v[92:95], v[12:13], v[164:165], 0
	v_mfma_f32_16x16x32_fp8_fp8 v[96:99], v[16:17], v[164:165], 0
	v_mfma_f32_16x16x32_fp8_fp8 v[84:87], v[4:5], v[166:167], v[84:87]
	v_mfma_f32_16x16x32_fp8_fp8 v[88:91], v[8:9], v[166:167], v[88:91]
	v_mfma_f32_16x16x32_fp8_fp8 v[92:95], v[14:15], v[166:167], v[92:95]
	v_mfma_f32_16x16x32_fp8_fp8 v[96:99], v[18:19], v[166:167], v[96:99]
	v_and_b32_e32 v199, s29, v244
	s_cmp_eq_u32 s50, 1
	v_cmp_ne_u32_e32 vcc, 0, v199
	s_cbranch_scc1 .Lbm3_Ag0_near
	v_add_f32_e32 v200, v81, v190
	v_cndmask_b32_e32 v200, v77, v200, vcc
	s_cmp_eq_u32 s35, 0
	s_cbranch_scc1 .Lbm3_Ag0_first
	v_pk_fma_f32 v[84:85], v[84:85], s[10:11], v[200:201] op_sel_hi:[1,1,0]
	v_pk_fma_f32 v[86:87], v[86:87], s[10:11], v[200:201] op_sel_hi:[1,1,0]
	v_pk_fma_f32 v[88:89], v[88:89], s[10:11], v[200:201] op_sel_hi:[1,1,0]
	v_pk_fma_f32 v[90:91], v[90:91], s[10:11], v[200:201] op_sel_hi:[1,1,0]
	v_exp_f32_e32 v84, v84
	v_exp_f32_e32 v85, v85
	v_exp_f32_e32 v86, v86
	v_exp_f32_e32 v87, v87
	v_pk_fma_f32 v[92:93], v[92:93], s[10:11], v[200:201] op_sel_hi:[1,1,0]
	v_pk_fma_f32 v[94:95], v[94:95], s[10:11], v[200:201] op_sel_hi:[1,1,0]
	v_exp_f32_e32 v88, v88
	v_exp_f32_e32 v89, v89
	v_exp_f32_e32 v90, v90
	v_exp_f32_e32 v91, v91
	v_pk_fma_f32 v[96:97], v[96:97], s[10:11], v[200:201] op_sel_hi:[1,1,0]
	v_pk_fma_f32 v[98:99], v[98:99], s[10:11], v[200:201] op_sel_hi:[1,1,0]
	v_exp_f32_e32 v92, v92
	v_exp_f32_e32 v93, v93
	v_exp_f32_e32 v94, v94
	v_exp_f32_e32 v95, v95
	s_nop 0
	v_exp_f32_e32 v96, v96
	v_exp_f32_e32 v97, v97
	v_exp_f32_e32 v98, v98
	v_exp_f32_e32 v99, v99
	v_pk_add_f32 v[248:249], v[84:85], v[86:87]
	v_pk_add_f32 v[82:83], v[88:89], v[90:91]
	v_pk_add_f32 v[172:173], v[92:93], v[94:95]
	v_pk_add_f32 v[202:203], v[96:97], v[98:99]
	v_cvt_pk_fp8_f32 v84, v84, v85
	v_cvt_pk_fp8_f32 v85, v88, v89
	v_pk_add_f32 v[248:249], v[248:249], v[82:83]
	v_pk_add_f32 v[172:173], v[172:173], v[202:203]
	v_cvt_pk_fp8_f32 v84, v86, v87 op_sel:[0,0,1]
	v_cvt_pk_fp8_f32 v85, v90, v91 op_sel:[0,0,1]
	v_pk_add_f32 v[248:249], v[248:249], v[172:173]
	v_cvt_pk_fp8_f32 v86, v92, v93
	v_cvt_pk_fp8_f32 v87, v96, v97
	v_add_f32_e32 v248, v248, v249
	v_cvt_pk_fp8_f32 v86, v94, v95 op_sel:[0,0,1]
	v_cvt_pk_fp8_f32 v87, v98, v99 op_sel:[0,0,1]
	v_cmp_lt_f32_e32 vcc, 0x43800000, v248
	s_cbranch_vccnz .Lbm3_Ag0_redo
	v_add_f32_e32 v194, v194, v248
	s_waitcnt vmcnt(8)
	v_mfma_f32_16x16x32_fp8_fp8 v[100:103], v[36:37], v[84:85], v[100:103]
	v_mfma_f32_16x16x32_fp8_fp8 v[104:107], v[38:39], v[84:85], v[104:107]
	v_mfma_f32_16x16x32_fp8_fp8 v[108:111], v[40:41], v[84:85], v[108:111]
	v_mfma_f32_16x16x32_fp8_fp8 v[112:115], v[42:43], v[84:85], v[112:115]
	v_mfma_f32_16x16x32_fp8_fp8 v[100:103], v[44:45], v[86:87], v[100:103]
	v_mfma_f32_16x16x32_fp8_fp8 v[104:107], v[46:47], v[86:87], v[104:107]
	v_mfma_f32_16x16x32_fp8_fp8 v[108:111], v[48:49], v[86:87], v[108:111]
	v_mfma_f32_16x16x32_fp8_fp8 v[112:115], v[50:51], v[86:87], v[112:115]
	s_branch .Lbm3_Ag0_skip

.Lbm3_Ag0_first:
	v_pk_fma_f32 v[84:85], v[84:85], s[10:11], v[200:201] op_sel_hi:[1,1,0]
	v_pk_fma_f32 v[86:87], v[86:87], s[10:11], v[200:201] op_sel_hi:[1,1,0]
	v_pk_fma_f32 v[88:89], v[88:89], s[10:11], v[200:201] op_sel_hi:[1,1,0]
	v_pk_fma_f32 v[90:91], v[90:91], s[10:11], v[200:201] op_sel_hi:[1,1,0]
	v_pk_fma_f32 v[92:93], v[92:93], s[10:11], v[200:201] op_sel_hi:[1,1,0]
	v_pk_fma_f32 v[94:95], v[94:95], s[10:11], v[200:201] op_sel_hi:[1,1,0]
	v_pk_fma_f32 v[96:97], v[96:97], s[10:11], v[200:201] op_sel_hi:[1,1,0]
	v_pk_fma_f32 v[98:99], v[98:99], s[10:11], v[200:201] op_sel_hi:[1,1,0]

.Lbm3_Ag0_skip:
	s_bfe_u32 s29, s48, 0x40004
	s_cmp_eq_u32 s29, 0
	s_cbranch_scc1 .Lbm3_Ag1_skip
	s_waitcnt vmcnt(12)
	v_mfma_f32_16x16x32_fp8_fp8 v[84:87], v[2:3], v[168:169], 0
	v_mfma_f32_16x16x32_fp8_fp8 v[88:91], v[6:7], v[168:169], 0
	v_mfma_f32_16x16x32_fp8_fp8 v[92:95], v[12:13], v[168:169], 0
	v_mfma_f32_16x16x32_fp8_fp8 v[96:99], v[16:17], v[168:169], 0
	v_mfma_f32_16x16x32_fp8_fp8 v[84:87], v[4:5], v[170:171], v[84:87]
	v_mfma_f32_16x16x32_fp8_fp8 v[88:91], v[8:9], v[170:171], v[88:91]
	v_mfma_f32_16x16x32_fp8_fp8 v[92:95], v[14:15], v[170:171], v[92:95]
	v_mfma_f32_16x16x32_fp8_fp8 v[96:99], v[18:19], v[170:171], v[96:99]
	v_and_b32_e32 v199, s29, v244
	s_cmp_eq_u32 s50, 1
	v_cmp_ne_u32_e32 vcc, 0, v199
	s_cbranch_scc1 .Lbm3_Ag1_near
	v_add_f32_e32 v200, v81, v191
	v_cndmask_b32_e32 v200, v77, v200, vcc
	s_cmp_eq_u32 s35, 0
	s_cbranch_scc1 .Lbm3_Ag1_first
	v_pk_fma_f32 v[84:85], v[84:85], s[10:11], v[200:201] op_sel_hi:[1,1,0]
	v_pk_fma_f32 v[86:87], v[86:87], s[10:11], v[200:201] op_sel_hi:[1,1,0]
	v_pk_fma_f32 v[88:89], v[88:89], s[10:11], v[200:201] op_sel_hi:[1,1,0]
	v_pk_fma_f32 v[90:91], v[90:91], s[10:11], v[200:201] op_sel_hi:[1,1,0]
	v_exp_f32_e32 v84, v84
	v_exp_f32_e32 v85, v85
	v_exp_f32_e32 v86, v86
	v_exp_f32_e32 v87, v87
	v_pk_fma_f32 v[92:93], v[92:93], s[10:11], v[200:201] op_sel_hi:[1,1,0]
	v_pk_fma_f32 v[94:95], v[94:95], s[10:11], v[200:201] op_sel_hi:[1,1,0]
	v_exp_f32_e32 v88, v88
	v_exp_f32_e32 v89, v89
	v_exp_f32_e32 v90, v90
	v_exp_f32_e32 v91, v91
	v_pk_fma_f32 v[96:97], v[96:97], s[10:11], v[200:201] op_sel_hi:[1,1,0]
	v_pk_fma_f32 v[98:99], v[98:99], s[10:11], v[200:201] op_sel_hi:[1,1,0]
	v_exp_f32_e32 v92, v92
	v_exp_f32_e32 v93, v93
	v_exp_f32_e32 v94, v94
	v_exp_f32_e32 v95, v95
	s_nop 0
	v_exp_f32_e32 v96, v96
	v_exp_f32_e32 v97, v97
	v_exp_f32_e32 v98, v98
	v_exp_f32_e32 v99, v99
	v_pk_add_f32 v[248:249], v[84:85], v[86:87]
	v_pk_add_f32 v[82:83], v[88:89], v[90:91]
	v_pk_add_f32 v[172:173], v[92:93], v[94:95]
	v_pk_add_f32 v[202:203], v[96:97], v[98:99]
	v_cvt_pk_fp8_f32 v84, v84, v85
	v_cvt_pk_fp8_f32 v85, v88, v89
	v_pk_add_f32 v[248:249], v[248:249], v[82:83]
	v_pk_add_f32 v[172:173], v[172:173], v[202:203]
	v_cvt_pk_fp8_f32 v84, v86, v87 op_sel:[0,0,1]
	v_cvt_pk_fp8_f32 v85, v90, v91 op_sel:[0,0,1]
	v_pk_add_f32 v[248:249], v[248:249], v[172:173]
	v_cvt_pk_fp8_f32 v86, v92, v93
	v_cvt_pk_fp8_f32 v87, v96, v97
	v_add_f32_e32 v248, v248, v249
	v_cvt_pk_fp8_f32 v86, v94, v95 op_sel:[0,0,1]
	v_cvt_pk_fp8_f32 v87, v98, v99 op_sel:[0,0,1]
	v_cmp_lt_f32_e32 vcc, 0x43800000, v248
	s_cbranch_vccnz .Lbm3_Ag1_redo
	v_add_f32_e32 v195, v195, v248
	s_waitcnt vmcnt(8)
	v_mfma_f32_16x16x32_fp8_fp8 v[116:119], v[36:37], v[84:85], v[116:119]
	v_mfma_f32_16x16x32_fp8_fp8 v[120:123], v[38:39], v[84:85], v[120:123]
	v_mfma_f32_16x16x32_fp8_fp8 v[124:127], v[40:41], v[84:85], v[124:127]
	v_mfma_f32_16x16x32_fp8_fp8 v[128:131], v[42:43], v[84:85], v[128:131]
	v_mfma_f32_16x16x32_fp8_fp8 v[116:119], v[44:45], v[86:87], v[116:119]
	v_mfma_f32_16x16x32_fp8_fp8 v[120:123], v[46:47], v[86:87], v[120:123]
	v_mfma_f32_16x16x32_fp8_fp8 v[124:127], v[48:49], v[86:87], v[124:127]
	v_mfma_f32_16x16x32_fp8_fp8 v[128:131], v[50:51], v[86:87], v[128:131]
	s_branch .Lbm3_Ag1_skip

.Lbm3_Ag1_skip:
	s_bfe_u32 s29, s48, 0x40008
	s_cmp_eq_u32 s29, 0
	s_cbranch_scc1 .Lbm3_Ag2_skip
	s_waitcnt vmcnt(12)
	v_mfma_f32_16x16x32_fp8_fp8 v[84:87], v[2:3], v[182:183], 0
	v_mfma_f32_16x16x32_fp8_fp8 v[88:91], v[6:7], v[182:183], 0
	v_mfma_f32_16x16x32_fp8_fp8 v[92:95], v[12:13], v[182:183], 0
	v_mfma_f32_16x16x32_fp8_fp8 v[96:99], v[16:17], v[182:183], 0
	v_mfma_f32_16x16x32_fp8_fp8 v[84:87], v[4:5], v[184:185], v[84:87]
	v_mfma_f32_16x16x32_fp8_fp8 v[88:91], v[8:9], v[184:185], v[88:91]
	v_mfma_f32_16x16x32_fp8_fp8 v[92:95], v[14:15], v[184:185], v[92:95]
	v_mfma_f32_16x16x32_fp8_fp8 v[96:99], v[18:19], v[184:185], v[96:99]
	v_and_b32_e32 v199, s29, v244
	s_cmp_eq_u32 s50, 1
	v_cmp_ne_u32_e32 vcc, 0, v199
	s_cbranch_scc1 .Lbm3_Ag2_near
	v_add_f32_e32 v200, v81, v192
	v_cndmask_b32_e32 v200, v77, v200, vcc
	s_cmp_eq_u32 s35, 0
	s_cbranch_scc1 .Lbm3_Ag2_first
	v_pk_fma_f32 v[84:85], v[84:85], s[10:11], v[200:201] op_sel_hi:[1,1,0]
	v_pk_fma_f32 v[86:87], v[86:87], s[10:11], v[200:201] op_sel_hi:[1,1,0]
	v_pk_fma_f32 v[88:89], v[88:89], s[10:11], v[200:201] op_sel_hi:[1,1,0]
	v_pk_fma_f32 v[90:91], v[90:91], s[10:11], v[200:201] op_sel_hi:[1,1,0]
	v_exp_f32_e32 v84, v84
	v_exp_f32_e32 v85, v85
	v_exp_f32_e32 v86, v86
	v_exp_f32_e32 v87, v87
	v_pk_fma_f32 v[92:93], v[92:93], s[10:11], v[200:201] op_sel_hi:[1,1,0]
	v_pk_fma_f32 v[94:95], v[94:95], s[10:11], v[200:201] op_sel_hi:[1,1,0]
	v_exp_f32_e32 v88, v88
	v_exp_f32_e32 v89, v89
	v_exp_f32_e32 v90, v90
	v_exp_f32_e32 v91, v91
	v_pk_fma_f32 v[96:97], v[96:97], s[10:11], v[200:201] op_sel_hi:[1,1,0]
	v_pk_fma_f32 v[98:99], v[98:99], s[10:11], v[200:201] op_sel_hi:[1,1,0]
	v_exp_f32_e32 v92, v92
	v_exp_f32_e32 v93, v93
	v_exp_f32_e32 v94, v94
	v_exp_f32_e32 v95, v95
	s_nop 0
	v_exp_f32_e32 v96, v96
	v_exp_f32_e32 v97, v97
	v_exp_f32_e32 v98, v98
	v_exp_f32_e32 v99, v99
	v_pk_add_f32 v[248:249], v[84:85], v[86:87]
	v_pk_add_f32 v[82:83], v[88:89], v[90:91]
	v_pk_add_f32 v[172:173], v[92:93], v[94:95]
	v_pk_add_f32 v[202:203], v[96:97], v[98:99]
	v_cvt_pk_fp8_f32 v84, v84, v85
	v_cvt_pk_fp8_f32 v85, v88, v89
	v_pk_add_f32 v[248:249], v[248:249], v[82:83]
	v_pk_add_f32 v[172:173], v[172:173], v[202:203]
	v_cvt_pk_fp8_f32 v84, v86, v87 op_sel:[0,0,1]
	v_cvt_pk_fp8_f32 v85, v90, v91 op_sel:[0,0,1]
	v_pk_add_f32 v[248:249], v[248:249], v[172:173]
	v_cvt_pk_fp8_f32 v86, v92, v93
	v_cvt_pk_fp8_f32 v87, v96, v97
	v_add_f32_e32 v248, v248, v249
	v_cvt_pk_fp8_f32 v86, v94, v95 op_sel:[0,0,1]
	v_cvt_pk_fp8_f32 v87, v98, v99 op_sel:[0,0,1]
	v_cmp_lt_f32_e32 vcc, 0x43800000, v248
	s_cbranch_vccnz .Lbm3_Ag2_redo
	v_add_f32_e32 v196, v196, v248
	s_waitcnt vmcnt(8)
	v_mfma_f32_16x16x32_fp8_fp8 v[132:135], v[36:37], v[84:85], v[132:135]
	v_mfma_f32_16x16x32_fp8_fp8 v[136:139], v[38:39], v[84:85], v[136:139]
	v_mfma_f32_16x16x32_fp8_fp8 v[140:143], v[40:41], v[84:85], v[140:143]
	v_mfma_f32_16x16x32_fp8_fp8 v[144:147], v[42:43], v[84:85], v[144:147]
	v_mfma_f32_16x16x32_fp8_fp8 v[132:135], v[44:45], v[86:87], v[132:135]
	v_mfma_f32_16x16x32_fp8_fp8 v[136:139], v[46:47], v[86:87], v[136:139]
	v_mfma_f32_16x16x32_fp8_fp8 v[140:143], v[48:49], v[86:87], v[140:143]
	v_mfma_f32_16x16x32_fp8_fp8 v[144:147], v[50:51], v[86:87], v[144:147]
	s_branch .Lbm3_Ag2_skip

.Lbm3_Ag2_skip:
	s_bfe_u32 s29, s48, 0x4000c
	s_cmp_eq_u32 s29, 0
	s_cbranch_scc1 .Lbm3_Ag3_skip
	s_waitcnt vmcnt(12)
	v_mfma_f32_16x16x32_fp8_fp8 v[84:87], v[2:3], v[186:187], 0
	v_mfma_f32_16x16x32_fp8_fp8 v[88:91], v[6:7], v[186:187], 0
	v_mfma_f32_16x16x32_fp8_fp8 v[92:95], v[12:13], v[186:187], 0
	v_mfma_f32_16x16x32_fp8_fp8 v[96:99], v[16:17], v[186:187], 0
	v_mfma_f32_16x16x32_fp8_fp8 v[84:87], v[4:5], v[188:189], v[84:87]
	v_mfma_f32_16x16x32_fp8_fp8 v[88:91], v[8:9], v[188:189], v[88:91]
	v_mfma_f32_16x16x32_fp8_fp8 v[92:95], v[14:15], v[188:189], v[92:95]
	v_mfma_f32_16x16x32_fp8_fp8 v[96:99], v[18:19], v[188:189], v[96:99]
	v_and_b32_e32 v199, s29, v244
	s_cmp_eq_u32 s50, 1
	v_cmp_ne_u32_e32 vcc, 0, v199
	s_cbranch_scc1 .Lbm3_Ag3_near
	v_add_f32_e32 v200, v81, v193
	v_cndmask_b32_e32 v200, v77, v200, vcc
	s_cmp_eq_u32 s35, 0
	s_cbranch_scc1 .Lbm3_Ag3_first
	v_pk_fma_f32 v[84:85], v[84:85], s[10:11], v[200:201] op_sel_hi:[1,1,0]
	v_pk_fma_f32 v[86:87], v[86:87], s[10:11], v[200:201] op_sel_hi:[1,1,0]
	v_pk_fma_f32 v[88:89], v[88:89], s[10:11], v[200:201] op_sel_hi:[1,1,0]
	v_pk_fma_f32 v[90:91], v[90:91], s[10:11], v[200:201] op_sel_hi:[1,1,0]
	v_exp_f32_e32 v84, v84
	v_exp_f32_e32 v85, v85
	v_exp_f32_e32 v86, v86
	v_exp_f32_e32 v87, v87
	v_pk_fma_f32 v[92:93], v[92:93], s[10:11], v[200:201] op_sel_hi:[1,1,0]
	v_pk_fma_f32 v[94:95], v[94:95], s[10:11], v[200:201] op_sel_hi:[1,1,0]
	v_exp_f32_e32 v88, v88
	v_exp_f32_e32 v89, v89
	v_exp_f32_e32 v90, v90
	v_exp_f32_e32 v91, v91
	v_pk_fma_f32 v[96:97], v[96:97], s[10:11], v[200:201] op_sel_hi:[1,1,0]
	v_pk_fma_f32 v[98:99], v[98:99], s[10:11], v[200:201] op_sel_hi:[1,1,0]
	v_exp_f32_e32 v92, v92
	v_exp_f32_e32 v93, v93
	v_exp_f32_e32 v94, v94
	v_exp_f32_e32 v95, v95
	s_nop 0
	v_exp_f32_e32 v96, v96
	v_exp_f32_e32 v97, v97
	v_exp_f32_e32 v98, v98
	v_exp_f32_e32 v99, v99
	v_pk_add_f32 v[248:249], v[84:85], v[86:87]
	v_pk_add_f32 v[82:83], v[88:89], v[90:91]
	v_pk_add_f32 v[172:173], v[92:93], v[94:95]
	v_pk_add_f32 v[202:203], v[96:97], v[98:99]
	v_cvt_pk_fp8_f32 v84, v84, v85
	v_cvt_pk_fp8_f32 v85, v88, v89
	v_pk_add_f32 v[248:249], v[248:249], v[82:83]
	v_pk_add_f32 v[172:173], v[172:173], v[202:203]
	v_cvt_pk_fp8_f32 v84, v86, v87 op_sel:[0,0,1]
	v_cvt_pk_fp8_f32 v85, v90, v91 op_sel:[0,0,1]
	v_pk_add_f32 v[248:249], v[248:249], v[172:173]
	v_cvt_pk_fp8_f32 v86, v92, v93
	v_cvt_pk_fp8_f32 v87, v96, v97
	v_add_f32_e32 v248, v248, v249
	v_cvt_pk_fp8_f32 v86, v94, v95 op_sel:[0,0,1]
	v_cvt_pk_fp8_f32 v87, v98, v99 op_sel:[0,0,1]
	v_cmp_lt_f32_e32 vcc, 0x43800000, v248
	s_cbranch_vccnz .Lbm3_Ag3_redo
	v_add_f32_e32 v197, v197, v248
	s_waitcnt vmcnt(8)
	v_mfma_f32_16x16x32_fp8_fp8 v[148:151], v[36:37], v[84:85], v[148:151]
	v_mfma_f32_16x16x32_fp8_fp8 v[152:155], v[38:39], v[84:85], v[152:155]
	v_mfma_f32_16x16x32_fp8_fp8 v[156:159], v[40:41], v[84:85], v[156:159]
	v_mfma_f32_16x16x32_fp8_fp8 v[160:163], v[42:43], v[84:85], v[160:163]
	v_mfma_f32_16x16x32_fp8_fp8 v[148:151], v[44:45], v[86:87], v[148:151]
	v_mfma_f32_16x16x32_fp8_fp8 v[152:155], v[46:47], v[86:87], v[152:155]
	v_mfma_f32_16x16x32_fp8_fp8 v[156:159], v[48:49], v[86:87], v[156:159]
	v_mfma_f32_16x16x32_fp8_fp8 v[160:163], v[50:51], v[86:87], v[160:163]
	s_branch .Lbm3_Ag3_skip

.Lbm3_blkB:
	s_lshl_b32 s29, s27, 12
	s_add_u32 s30, s40, s29
	s_addc_u32 s31, s41, 0
	global_load_dwordx4 v[2:5], v79, s[30:31]
	global_load_dwordx4 v[6:9], v79, s[30:31] offset:1024
	global_load_dwordx4 v[12:15], v79, s[30:31] offset:2048
	global_load_dwordx4 v[16:19], v79, s[30:31] offset:3072
	s_lshl_b32 s29, s27, 12
	s_add_u32 s30, s62, s29
	s_addc_u32 s31, s63, 0
	global_load_dwordx4 v[36:39], v79, s[30:31]
	global_load_dwordx4 v[40:43], v79, s[30:31] offset:1024
	global_load_dwordx4 v[44:47], v79, s[30:31] offset:2048
	global_load_dwordx4 v[48:51], v79, s[30:31] offset:3072
	s_add_i32 s50, s35, 2
	s_add_i32 s9, s25, -1
	s_min_i32 s50, s50, s9
	s_lshl_b32 s9, s50, 2
	s_add_i32 s9, s9, s46
	v_mov_b32_e32 v76, s9
	ds_read_b32 v76, v76 offset:16384
	s_cmp_ge_i32 s38, s21
	s_cselect_b32 s50, 1, 0
	s_bfe_u32 s29, s48, 0x40000
	s_cmp_eq_u32 s29, 0
	s_cbranch_scc1 .Lbm3_Bg0_skip
	s_waitcnt vmcnt(12)
	v_mfma_f32_16x16x32_fp8_fp8 v[84:87], v[20:21], v[164:165], 0
	v_mfma_f32_16x16x32_fp8_fp8 v[88:91], v[24:25], v[164:165], 0
	v_mfma_f32_16x16x32_fp8_fp8 v[92:95], v[28:29], v[164:165], 0
	v_mfma_f32_16x16x32_fp8_fp8 v[96:99], v[32:33], v[164:165], 0
	v_mfma_f32_16x16x32_fp8_fp8 v[84:87], v[22:23], v[166:167], v[84:87]
	v_mfma_f32_16x16x32_fp8_fp8 v[88:91], v[26:27], v[166:167], v[88:91]
	v_mfma_f32_16x16x32_fp8_fp8 v[92:95], v[30:31], v[166:167], v[92:95]
	v_mfma_f32_16x16x32_fp8_fp8 v[96:99], v[34:35], v[166:167], v[96:99]
	v_and_b32_e32 v199, s29, v244
	s_cmp_eq_u32 s50, 1
	v_cmp_ne_u32_e32 vcc, 0, v199
	s_cbranch_scc1 .Lbm3_Bg0_near
	v_add_f32_e32 v200, v81, v190
	v_cndmask_b32_e32 v200, v77, v200, vcc
	s_cmp_eq_u32 s35, 0
	s_cbranch_scc1 .Lbm3_Bg0_first
	v_pk_fma_f32 v[84:85], v[84:85], s[10:11], v[200:201] op_sel_hi:[1,1,0]
	v_pk_fma_f32 v[86:87], v[86:87], s[10:11], v[200:201] op_sel_hi:[1,1,0]
	v_pk_fma_f32 v[88:89], v[88:89], s[10:11], v[200:201] op_sel_hi:[1,1,0]
	v_pk_fma_f32 v[90:91], v[90:91], s[10:11], v[200:201] op_sel_hi:[1,1,0]
	v_exp_f32_e32 v84, v84
	v_exp_f32_e32 v85, v85
	v_exp_f32_e32 v86, v86
	v_exp_f32_e32 v87, v87
	v_pk_fma_f32 v[92:93], v[92:93], s[10:11], v[200:201] op_sel_hi:[1,1,0]
	v_pk_fma_f32 v[94:95], v[94:95], s[10:11], v[200:201] op_sel_hi:[1,1,0]
	v_exp_f32_e32 v88, v88
	v_exp_f32_e32 v89, v89
	v_exp_f32_e32 v90, v90
	v_exp_f32_e32 v91, v91
	v_pk_fma_f32 v[96:97], v[96:97], s[10:11], v[200:201] op_sel_hi:[1,1,0]
	v_pk_fma_f32 v[98:99], v[98:99], s[10:11], v[200:201] op_sel_hi:[1,1,0]
	v_exp_f32_e32 v92, v92
	v_exp_f32_e32 v93, v93
	v_exp_f32_e32 v94, v94
	v_exp_f32_e32 v95, v95
	s_nop 0
	v_exp_f32_e32 v96, v96
	v_exp_f32_e32 v97, v97
	v_exp_f32_e32 v98, v98
	v_exp_f32_e32 v99, v99
	v_pk_add_f32 v[248:249], v[84:85], v[86:87]
	v_pk_add_f32 v[82:83], v[88:89], v[90:91]
	v_pk_add_f32 v[172:173], v[92:93], v[94:95]
	v_pk_add_f32 v[202:203], v[96:97], v[98:99]
	v_cvt_pk_fp8_f32 v84, v84, v85
	v_cvt_pk_fp8_f32 v85, v88, v89
	v_pk_add_f32 v[248:249], v[248:249], v[82:83]
	v_pk_add_f32 v[172:173], v[172:173], v[202:203]
	v_cvt_pk_fp8_f32 v84, v86, v87 op_sel:[0,0,1]
	v_cvt_pk_fp8_f32 v85, v90, v91 op_sel:[0,0,1]
	v_pk_add_f32 v[248:249], v[248:249], v[172:173]
	v_cvt_pk_fp8_f32 v86, v92, v93
	v_cvt_pk_fp8_f32 v87, v96, v97
	v_add_f32_e32 v248, v248, v249
	v_cvt_pk_fp8_f32 v86, v94, v95 op_sel:[0,0,1]
	v_cvt_pk_fp8_f32 v87, v98, v99 op_sel:[0,0,1]
	v_cmp_lt_f32_e32 vcc, 0x43800000, v248
	s_cbranch_vccnz .Lbm3_Bg0_redo
	v_add_f32_e32 v194, v194, v248
	s_waitcnt vmcnt(8)
	v_mfma_f32_16x16x32_fp8_fp8 v[100:103], v[52:53], v[84:85], v[100:103]
	v_mfma_f32_16x16x32_fp8_fp8 v[104:107], v[54:55], v[84:85], v[104:107]
	v_mfma_f32_16x16x32_fp8_fp8 v[108:111], v[56:57], v[84:85], v[108:111]
	v_mfma_f32_16x16x32_fp8_fp8 v[112:115], v[58:59], v[84:85], v[112:115]
	v_mfma_f32_16x16x32_fp8_fp8 v[100:103], v[60:61], v[86:87], v[100:103]
	v_mfma_f32_16x16x32_fp8_fp8 v[104:107], v[62:63], v[86:87], v[104:107]
	v_mfma_f32_16x16x32_fp8_fp8 v[108:111], v[64:65], v[86:87], v[108:111]
	v_mfma_f32_16x16x32_fp8_fp8 v[112:115], v[66:67], v[86:87], v[112:115]
	s_branch .Lbm3_Bg0_skip

.Lbm3_Bg0_skip:
	s_bfe_u32 s29, s48, 0x40004
	s_cmp_eq_u32 s29, 0
	s_cbranch_scc1 .Lbm3_Bg1_skip
	s_waitcnt vmcnt(12)
	v_mfma_f32_16x16x32_fp8_fp8 v[84:87], v[20:21], v[168:169], 0
	v_mfma_f32_16x16x32_fp8_fp8 v[88:91], v[24:25], v[168:169], 0
	v_mfma_f32_16x16x32_fp8_fp8 v[92:95], v[28:29], v[168:169], 0
	v_mfma_f32_16x16x32_fp8_fp8 v[96:99], v[32:33], v[168:169], 0
	v_mfma_f32_16x16x32_fp8_fp8 v[84:87], v[22:23], v[170:171], v[84:87]
	v_mfma_f32_16x16x32_fp8_fp8 v[88:91], v[26:27], v[170:171], v[88:91]
	v_mfma_f32_16x16x32_fp8_fp8 v[92:95], v[30:31], v[170:171], v[92:95]
	v_mfma_f32_16x16x32_fp8_fp8 v[96:99], v[34:35], v[170:171], v[96:99]
	v_and_b32_e32 v199, s29, v244
	s_cmp_eq_u32 s50, 1
	v_cmp_ne_u32_e32 vcc, 0, v199
	s_cbranch_scc1 .Lbm3_Bg1_near
	v_add_f32_e32 v200, v81, v191
	v_cndmask_b32_e32 v200, v77, v200, vcc
	s_cmp_eq_u32 s35, 0
	s_cbranch_scc1 .Lbm3_Bg1_first
	v_pk_fma_f32 v[84:85], v[84:85], s[10:11], v[200:201] op_sel_hi:[1,1,0]
	v_pk_fma_f32 v[86:87], v[86:87], s[10:11], v[200:201] op_sel_hi:[1,1,0]
	v_pk_fma_f32 v[88:89], v[88:89], s[10:11], v[200:201] op_sel_hi:[1,1,0]
	v_pk_fma_f32 v[90:91], v[90:91], s[10:11], v[200:201] op_sel_hi:[1,1,0]
	v_exp_f32_e32 v84, v84
	v_exp_f32_e32 v85, v85
	v_exp_f32_e32 v86, v86
	v_exp_f32_e32 v87, v87
	v_pk_fma_f32 v[92:93], v[92:93], s[10:11], v[200:201] op_sel_hi:[1,1,0]
	v_pk_fma_f32 v[94:95], v[94:95], s[10:11], v[200:201] op_sel_hi:[1,1,0]
	v_exp_f32_e32 v88, v88
	v_exp_f32_e32 v89, v89
	v_exp_f32_e32 v90, v90
	v_exp_f32_e32 v91, v91
	v_pk_fma_f32 v[96:97], v[96:97], s[10:11], v[200:201] op_sel_hi:[1,1,0]
	v_pk_fma_f32 v[98:99], v[98:99], s[10:11], v[200:201] op_sel_hi:[1,1,0]
	v_exp_f32_e32 v92, v92
	v_exp_f32_e32 v93, v93
	v_exp_f32_e32 v94, v94
	v_exp_f32_e32 v95, v95
	s_nop 0
	v_exp_f32_e32 v96, v96
	v_exp_f32_e32 v97, v97
	v_exp_f32_e32 v98, v98
	v_exp_f32_e32 v99, v99
	v_pk_add_f32 v[248:249], v[84:85], v[86:87]
	v_pk_add_f32 v[82:83], v[88:89], v[90:91]
	v_pk_add_f32 v[172:173], v[92:93], v[94:95]
	v_pk_add_f32 v[202:203], v[96:97], v[98:99]
	v_cvt_pk_fp8_f32 v84, v84, v85
	v_cvt_pk_fp8_f32 v85, v88, v89
	v_pk_add_f32 v[248:249], v[248:249], v[82:83]
	v_pk_add_f32 v[172:173], v[172:173], v[202:203]
	v_cvt_pk_fp8_f32 v84, v86, v87 op_sel:[0,0,1]
	v_cvt_pk_fp8_f32 v85, v90, v91 op_sel:[0,0,1]
	v_pk_add_f32 v[248:249], v[248:249], v[172:173]
	v_cvt_pk_fp8_f32 v86, v92, v93
	v_cvt_pk_fp8_f32 v87, v96, v97
	v_add_f32_e32 v248, v248, v249
	v_cvt_pk_fp8_f32 v86, v94, v95 op_sel:[0,0,1]
	v_cvt_pk_fp8_f32 v87, v98, v99 op_sel:[0,0,1]
	v_cmp_lt_f32_e32 vcc, 0x43800000, v248
	s_cbranch_vccnz .Lbm3_Bg1_redo
	v_add_f32_e32 v195, v195, v248
	s_waitcnt vmcnt(8)
	v_mfma_f32_16x16x32_fp8_fp8 v[116:119], v[52:53], v[84:85], v[116:119]
	v_mfma_f32_16x16x32_fp8_fp8 v[120:123], v[54:55], v[84:85], v[120:123]
	v_mfma_f32_16x16x32_fp8_fp8 v[124:127], v[56:57], v[84:85], v[124:127]
	v_mfma_f32_16x16x32_fp8_fp8 v[128:131], v[58:59], v[84:85], v[128:131]
	v_mfma_f32_16x16x32_fp8_fp8 v[116:119], v[60:61], v[86:87], v[116:119]
	v_mfma_f32_16x16x32_fp8_fp8 v[120:123], v[62:63], v[86:87], v[120:123]
	v_mfma_f32_16x16x32_fp8_fp8 v[124:127], v[64:65], v[86:87], v[124:127]
	v_mfma_f32_16x16x32_fp8_fp8 v[128:131], v[66:67], v[86:87], v[128:131]
	s_branch .Lbm3_Bg1_skip

.Lbm3_Bg1_skip:
	s_bfe_u32 s29, s48, 0x40008
	s_cmp_eq_u32 s29, 0
	s_cbranch_scc1 .Lbm3_Bg2_skip
	s_waitcnt vmcnt(12)
	v_mfma_f32_16x16x32_fp8_fp8 v[84:87], v[20:21], v[182:183], 0
	v_mfma_f32_16x16x32_fp8_fp8 v[88:91], v[24:25], v[182:183], 0
	v_mfma_f32_16x16x32_fp8_fp8 v[92:95], v[28:29], v[182:183], 0
	v_mfma_f32_16x16x32_fp8_fp8 v[96:99], v[32:33], v[182:183], 0
	v_mfma_f32_16x16x32_fp8_fp8 v[84:87], v[22:23], v[184:185], v[84:87]
	v_mfma_f32_16x16x32_fp8_fp8 v[88:91], v[26:27], v[184:185], v[88:91]
	v_mfma_f32_16x16x32_fp8_fp8 v[92:95], v[30:31], v[184:185], v[92:95]
	v_mfma_f32_16x16x32_fp8_fp8 v[96:99], v[34:35], v[184:185], v[96:99]
	v_and_b32_e32 v199, s29, v244
	s_cmp_eq_u32 s50, 1
	v_cmp_ne_u32_e32 vcc, 0, v199
	s_cbranch_scc1 .Lbm3_Bg2_near
	v_add_f32_e32 v200, v81, v192
	v_cndmask_b32_e32 v200, v77, v200, vcc
	s_cmp_eq_u32 s35, 0
	s_cbranch_scc1 .Lbm3_Bg2_first
	v_pk_fma_f32 v[84:85], v[84:85], s[10:11], v[200:201] op_sel_hi:[1,1,0]
	v_pk_fma_f32 v[86:87], v[86:87], s[10:11], v[200:201] op_sel_hi:[1,1,0]
	v_pk_fma_f32 v[88:89], v[88:89], s[10:11], v[200:201] op_sel_hi:[1,1,0]
	v_pk_fma_f32 v[90:91], v[90:91], s[10:11], v[200:201] op_sel_hi:[1,1,0]
	v_exp_f32_e32 v84, v84
	v_exp_f32_e32 v85, v85
	v_exp_f32_e32 v86, v86
	v_exp_f32_e32 v87, v87
	v_pk_fma_f32 v[92:93], v[92:93], s[10:11], v[200:201] op_sel_hi:[1,1,0]
	v_pk_fma_f32 v[94:95], v[94:95], s[10:11], v[200:201] op_sel_hi:[1,1,0]
	v_exp_f32_e32 v88, v88
	v_exp_f32_e32 v89, v89
	v_exp_f32_e32 v90, v90
	v_exp_f32_e32 v91, v91
	v_pk_fma_f32 v[96:97], v[96:97], s[10:11], v[200:201] op_sel_hi:[1,1,0]
	v_pk_fma_f32 v[98:99], v[98:99], s[10:11], v[200:201] op_sel_hi:[1,1,0]
	v_exp_f32_e32 v92, v92
	v_exp_f32_e32 v93, v93
	v_exp_f32_e32 v94, v94
	v_exp_f32_e32 v95, v95
	s_nop 0
	v_exp_f32_e32 v96, v96
	v_exp_f32_e32 v97, v97
	v_exp_f32_e32 v98, v98
	v_exp_f32_e32 v99, v99
	v_pk_add_f32 v[248:249], v[84:85], v[86:87]
	v_pk_add_f32 v[82:83], v[88:89], v[90:91]
	v_pk_add_f32 v[172:173], v[92:93], v[94:95]
	v_pk_add_f32 v[202:203], v[96:97], v[98:99]
	v_cvt_pk_fp8_f32 v84, v84, v85
	v_cvt_pk_fp8_f32 v85, v88, v89
	v_pk_add_f32 v[248:249], v[248:249], v[82:83]
	v_pk_add_f32 v[172:173], v[172:173], v[202:203]
	v_cvt_pk_fp8_f32 v84, v86, v87 op_sel:[0,0,1]
	v_cvt_pk_fp8_f32 v85, v90, v91 op_sel:[0,0,1]
	v_pk_add_f32 v[248:249], v[248:249], v[172:173]
	v_cvt_pk_fp8_f32 v86, v92, v93
	v_cvt_pk_fp8_f32 v87, v96, v97
	v_add_f32_e32 v248, v248, v249
	v_cvt_pk_fp8_f32 v86, v94, v95 op_sel:[0,0,1]
	v_cvt_pk_fp8_f32 v87, v98, v99 op_sel:[0,0,1]
	v_cmp_lt_f32_e32 vcc, 0x43800000, v248
	s_cbranch_vccnz .Lbm3_Bg2_redo
	v_add_f32_e32 v196, v196, v248
	s_waitcnt vmcnt(8)
	v_mfma_f32_16x16x32_fp8_fp8 v[132:135], v[52:53], v[84:85], v[132:135]
	v_mfma_f32_16x16x32_fp8_fp8 v[136:139], v[54:55], v[84:85], v[136:139]
	v_mfma_f32_16x16x32_fp8_fp8 v[140:143], v[56:57], v[84:85], v[140:143]
	v_mfma_f32_16x16x32_fp8_fp8 v[144:147], v[58:59], v[84:85], v[144:147]
	v_mfma_f32_16x16x32_fp8_fp8 v[132:135], v[60:61], v[86:87], v[132:135]
	v_mfma_f32_16x16x32_fp8_fp8 v[136:139], v[62:63], v[86:87], v[136:139]
	v_mfma_f32_16x16x32_fp8_fp8 v[140:143], v[64:65], v[86:87], v[140:143]
	v_mfma_f32_16x16x32_fp8_fp8 v[144:147], v[66:67], v[86:87], v[144:147]
	s_branch .Lbm3_Bg2_skip

.Lbm3_Bg2_skip:
	s_bfe_u32 s29, s48, 0x4000c
	s_cmp_eq_u32 s29, 0
	s_cbranch_scc1 .Lbm3_Bg3_skip
	s_waitcnt vmcnt(12)
	v_mfma_f32_16x16x32_fp8_fp8 v[84:87], v[20:21], v[186:187], 0
	v_mfma_f32_16x16x32_fp8_fp8 v[88:91], v[24:25], v[186:187], 0
	v_mfma_f32_16x16x32_fp8_fp8 v[92:95], v[28:29], v[186:187], 0
	v_mfma_f32_16x16x32_fp8_fp8 v[96:99], v[32:33], v[186:187], 0
	v_mfma_f32_16x16x32_fp8_fp8 v[84:87], v[22:23], v[188:189], v[84:87]
	v_mfma_f32_16x16x32_fp8_fp8 v[88:91], v[26:27], v[188:189], v[88:91]
	v_mfma_f32_16x16x32_fp8_fp8 v[92:95], v[30:31], v[188:189], v[92:95]
	v_mfma_f32_16x16x32_fp8_fp8 v[96:99], v[34:35], v[188:189], v[96:99]
	v_and_b32_e32 v199, s29, v244
	s_cmp_eq_u32 s50, 1
	v_cmp_ne_u32_e32 vcc, 0, v199
	s_cbranch_scc1 .Lbm3_Bg3_near
	v_add_f32_e32 v200, v81, v193
	v_cndmask_b32_e32 v200, v77, v200, vcc
	s_cmp_eq_u32 s35, 0
	s_cbranch_scc1 .Lbm3_Bg3_first
	v_pk_fma_f32 v[84:85], v[84:85], s[10:11], v[200:201] op_sel_hi:[1,1,0]
	v_pk_fma_f32 v[86:87], v[86:87], s[10:11], v[200:201] op_sel_hi:[1,1,0]
	v_pk_fma_f32 v[88:89], v[88:89], s[10:11], v[200:201] op_sel_hi:[1,1,0]
	v_pk_fma_f32 v[90:91], v[90:91], s[10:11], v[200:201] op_sel_hi:[1,1,0]
	v_exp_f32_e32 v84, v84
	v_exp_f32_e32 v85, v85
	v_exp_f32_e32 v86, v86
	v_exp_f32_e32 v87, v87
	v_pk_fma_f32 v[92:93], v[92:93], s[10:11], v[200:201] op_sel_hi:[1,1,0]
	v_pk_fma_f32 v[94:95], v[94:95], s[10:11], v[200:201] op_sel_hi:[1,1,0]
	v_exp_f32_e32 v88, v88
	v_exp_f32_e32 v89, v89
	v_exp_f32_e32 v90, v90
	v_exp_f32_e32 v91, v91
	v_pk_fma_f32 v[96:97], v[96:97], s[10:11], v[200:201] op_sel_hi:[1,1,0]
	v_pk_fma_f32 v[98:99], v[98:99], s[10:11], v[200:201] op_sel_hi:[1,1,0]
	v_exp_f32_e32 v92, v92
	v_exp_f32_e32 v93, v93
	v_exp_f32_e32 v94, v94
	v_exp_f32_e32 v95, v95
	s_nop 0
	v_exp_f32_e32 v96, v96
	v_exp_f32_e32 v97, v97
	v_exp_f32_e32 v98, v98
	v_exp_f32_e32 v99, v99
	v_pk_add_f32 v[248:249], v[84:85], v[86:87]
	v_pk_add_f32 v[82:83], v[88:89], v[90:91]
	v_pk_add_f32 v[172:173], v[92:93], v[94:95]
	v_pk_add_f32 v[202:203], v[96:97], v[98:99]
	v_cvt_pk_fp8_f32 v84, v84, v85
	v_cvt_pk_fp8_f32 v85, v88, v89
	v_pk_add_f32 v[248:249], v[248:249], v[82:83]
	v_pk_add_f32 v[172:173], v[172:173], v[202:203]
	v_cvt_pk_fp8_f32 v84, v86, v87 op_sel:[0,0,1]
	v_cvt_pk_fp8_f32 v85, v90, v91 op_sel:[0,0,1]
	v_pk_add_f32 v[248:249], v[248:249], v[172:173]
	v_cvt_pk_fp8_f32 v86, v92, v93
	v_cvt_pk_fp8_f32 v87, v96, v97
	v_add_f32_e32 v248, v248, v249
	v_cvt_pk_fp8_f32 v86, v94, v95 op_sel:[0,0,1]
	v_cvt_pk_fp8_f32 v87, v98, v99 op_sel:[0,0,1]
	v_cmp_lt_f32_e32 vcc, 0x43800000, v248
	s_cbranch_vccnz .Lbm3_Bg3_redo
	v_add_f32_e32 v197, v197, v248
	s_waitcnt vmcnt(8)
	v_mfma_f32_16x16x32_fp8_fp8 v[148:151], v[52:53], v[84:85], v[148:151]
	v_mfma_f32_16x16x32_fp8_fp8 v[152:155], v[54:55], v[84:85], v[152:155]
	v_mfma_f32_16x16x32_fp8_fp8 v[156:159], v[56:57], v[84:85], v[156:159]
	v_mfma_f32_16x16x32_fp8_fp8 v[160:163], v[58:59], v[84:85], v[160:163]
	v_mfma_f32_16x16x32_fp8_fp8 v[148:151], v[60:61], v[86:87], v[148:151]
	v_mfma_f32_16x16x32_fp8_fp8 v[152:155], v[62:63], v[86:87], v[152:155]
	v_mfma_f32_16x16x32_fp8_fp8 v[156:159], v[64:65], v[86:87], v[156:159]
	v_mfma_f32_16x16x32_fp8_fp8 v[160:163], v[66:67], v[86:87], v[160:163]
	s_branch .Lbm3_Bg3_skip
